# adaLN GEMV keeps 16 weight rows in flight per trip; prep conversion loops overlap next item's loads
# baseline (speedup 1.0000x reference)
; __device__ __forceinline__ void phase_prep(const Params& p, LAS unsigned char* lds, int tid, int wave, int lane, int G) {
;     ...
;         const float* W = p.ada_w + (size_t)l * DM * 6144 + cgi * 256 + lane * 4;
;         f32x4 a0 = {0.f, 0.f, 0.f, 0.f}, a1 = {0.f, 0.f, 0.f, 0.f};
;         const int kb = wave * 256;
;         for (int k = kb; k < kb + 256; k += 8) {
;             f32x4 w[8];
; #pragma unroll
;             for (int i = 0; i < 8; ++i) w[i] = *(const f32x4*)(W + (size_t)(k + i) * 6144);
; #pragma unroll
;             for (int i = 0; i < 8; ++i) { a0 += w[i] * cact[k + i]; a1 += w[i] * cact[2048 + k + i]; }
.LBB0_22:
	v_add_co_u32_e32 v28, vcc, 0xfffd6000, v18
	v_mov_b32_e32 v14, s18
	s_nop 0
	v_addc_co_u32_e32 v29, vcc, -1, v19, vcc
	v_add_co_u32_e32 v32, vcc, 0xfffdc000, v18
	s_add_i32 s19, s19, 16
	s_nop 0
	v_addc_co_u32_e32 v33, vcc, -1, v19, vcc
	v_add_co_u32_e32 v36, vcc, 0xfffe2000, v18
	global_load_dwordx4 v[28:31], v[28:29], off
	s_nop 0
	global_load_dwordx4 v[32:35], v[32:33], off
	v_addc_co_u32_e32 v37, vcc, -1, v19, vcc
	v_add_co_u32_e32 v40, vcc, 0xfffe8000, v18
	s_add_i32 s18, s18, 32
	s_nop 0
	v_addc_co_u32_e32 v41, vcc, -1, v19, vcc
	v_add_co_u32_e32 v44, vcc, 0xfffee000, v18
	global_load_dwordx4 v[36:39], v[36:37], off
	s_nop 0
	global_load_dwordx4 v[40:43], v[40:41], off
	v_addc_co_u32_e32 v45, vcc, -1, v19, vcc
	v_add_co_u32_e32 v48, vcc, 0xffff4000, v18
	global_load_dwordx4 v[44:47], v[44:45], off
	s_nop 0
	v_addc_co_u32_e32 v49, vcc, -1, v19, vcc
	v_add_co_u32_e32 v52, vcc, 0xffffa000, v18
	global_load_dwordx4 v[48:51], v[48:49], off
	s_nop 0
	v_addc_co_u32_e32 v53, vcc, -1, v19, vcc
	global_load_dwordx4 v[52:55], v[52:53], off
	s_nop 0
	global_load_dwordx4 v[56:59], v[18:19], off
	v_add_co_u32_e32 v108, vcc, 0x6000, v18
	s_nop 1
	v_addc_co_u32_e32 v109, vcc, 0, v19, vcc
	global_load_dwordx4 v[108:111], v[108:109], off
	v_add_co_u32_e32 v112, vcc, 0xc000, v18
	s_nop 1
	v_addc_co_u32_e32 v113, vcc, 0, v19, vcc
	global_load_dwordx4 v[112:115], v[112:113], off
	v_add_co_u32_e32 v116, vcc, 0x12000, v18
	s_nop 1
	v_addc_co_u32_e32 v117, vcc, 0, v19, vcc
	global_load_dwordx4 v[116:119], v[116:117], off
	v_add_co_u32_e32 v120, vcc, 0x18000, v18
	s_nop 1
	v_addc_co_u32_e32 v121, vcc, 0, v19, vcc
	global_load_dwordx4 v[120:123], v[120:121], off
	v_add_co_u32_e32 v124, vcc, 0x1e000, v18
	s_nop 1
	v_addc_co_u32_e32 v125, vcc, 0, v19, vcc
	global_load_dwordx4 v[124:127], v[124:125], off
	v_add_co_u32_e32 v128, vcc, 0x24000, v18
	s_nop 1
	v_addc_co_u32_e32 v129, vcc, 0, v19, vcc
	global_load_dwordx4 v[128:131], v[128:129], off
	v_add_co_u32_e32 v132, vcc, 0x2a000, v18
	s_nop 1
	v_addc_co_u32_e32 v133, vcc, 0, v19, vcc
	global_load_dwordx4 v[132:135], v[132:133], off
	v_add_co_u32_e32 v136, vcc, 0x30000, v18
	s_nop 1
	v_addc_co_u32_e32 v137, vcc, 0, v19, vcc
	global_load_dwordx4 v[136:139], v[136:137], off
	ds_read_b128 v[60:63], v14
	ds_read_b128 v[64:67], v14 offset:8192
	ds_read_b128 v[68:71], v14 offset:16
	ds_read_b128 v[72:75], v14 offset:8208
	s_waitcnt lgkmcnt(3)
	v_mov_b32_e32 v14, v63
	s_waitcnt lgkmcnt(2)
	v_mov_b32_e32 v76, v67
	s_waitcnt lgkmcnt(1)
	v_mov_b32_e32 v78, v71
	s_waitcnt lgkmcnt(0)
	v_mov_b32_e32 v80, v75
	v_lshl_add_u64 v[18:19], v[18:19], 0, s[26:27]
	s_waitcnt vmcnt(15)
	v_pk_fma_f32 v[4:5], v[30:31], v[60:61], v[4:5] op_sel_hi:[1,0,1]
	v_pk_fma_f32 v[2:3], v[28:29], v[60:61], v[2:3] op_sel_hi:[1,0,1]
	v_pk_fma_f32 v[8:9], v[30:31], v[64:65], v[8:9] op_sel_hi:[1,0,1]
	v_pk_fma_f32 v[6:7], v[28:29], v[64:65], v[6:7] op_sel_hi:[1,0,1]
	s_waitcnt vmcnt(14)
	v_pk_fma_f32 v[4:5], v[34:35], v[60:61], v[4:5] op_sel:[0,1,0]
	v_pk_fma_f32 v[2:3], v[32:33], v[60:61], v[2:3] op_sel:[0,1,0]
	v_pk_fma_f32 v[8:9], v[34:35], v[64:65], v[8:9] op_sel:[0,1,0]
	v_pk_fma_f32 v[6:7], v[32:33], v[64:65], v[6:7] op_sel:[0,1,0]
	s_waitcnt vmcnt(13)
	v_pk_fma_f32 v[4:5], v[38:39], v[62:63], v[4:5] op_sel_hi:[1,0,1]
	v_pk_fma_f32 v[2:3], v[36:37], v[62:63], v[2:3] op_sel_hi:[1,0,1]
	v_pk_fma_f32 v[8:9], v[38:39], v[66:67], v[8:9] op_sel_hi:[1,0,1]
	v_pk_fma_f32 v[6:7], v[36:37], v[66:67], v[6:7] op_sel_hi:[1,0,1]
	s_waitcnt vmcnt(12)
	v_pk_fma_f32 v[4:5], v[42:43], v[14:15], v[4:5] op_sel_hi:[1,0,1]
	v_pk_fma_f32 v[2:3], v[40:41], v[14:15], v[2:3] op_sel_hi:[1,0,1]
	v_pk_fma_f32 v[8:9], v[42:43], v[76:77], v[8:9] op_sel_hi:[1,0,1]
	v_pk_fma_f32 v[6:7], v[40:41], v[76:77], v[6:7] op_sel_hi:[1,0,1]
	s_waitcnt vmcnt(11)
	v_pk_fma_f32 v[4:5], v[46:47], v[68:69], v[4:5] op_sel_hi:[1,0,1]
	v_pk_fma_f32 v[2:3], v[44:45], v[68:69], v[2:3] op_sel_hi:[1,0,1]
	v_pk_fma_f32 v[8:9], v[46:47], v[72:73], v[8:9] op_sel_hi:[1,0,1]
	v_pk_fma_f32 v[6:7], v[44:45], v[72:73], v[6:7] op_sel_hi:[1,0,1]
	s_waitcnt vmcnt(10)
	v_pk_fma_f32 v[4:5], v[50:51], v[68:69], v[4:5] op_sel:[0,1,0]
	v_pk_fma_f32 v[2:3], v[48:49], v[68:69], v[2:3] op_sel:[0,1,0]
	v_pk_fma_f32 v[8:9], v[50:51], v[72:73], v[8:9] op_sel:[0,1,0]
	v_pk_fma_f32 v[6:7], v[48:49], v[72:73], v[6:7] op_sel:[0,1,0]
	s_waitcnt vmcnt(9)
	v_pk_fma_f32 v[4:5], v[54:55], v[70:71], v[4:5] op_sel_hi:[1,0,1]
	v_pk_fma_f32 v[2:3], v[52:53], v[70:71], v[2:3] op_sel_hi:[1,0,1]
	v_pk_fma_f32 v[8:9], v[54:55], v[74:75], v[8:9] op_sel_hi:[1,0,1]
	v_pk_fma_f32 v[6:7], v[52:53], v[74:75], v[6:7] op_sel_hi:[1,0,1]
	s_waitcnt vmcnt(8)
; #define LAS __attribute__((address_space(3)))
; __device__ __forceinline__ void phase_prep(const Params& p, LAS unsigned char* lds, int tid, int wave, int lane, int G) {
;     ...
;         for (int k = kb; k < kb + 256; k += 8) {
;             f32x4 w[8];
; #pragma unroll
;             for (int i = 0; i < 8; ++i) w[i] = *(const f32x4*)(W + (size_t)(k + i) * 6144);
; #pragma unroll
;             for (int i = 0; i < 8; ++i) { a0 += w[i] * cact[k + i]; a1 += w[i] * cact[2048 + k + i]; }
;         }
;         *(LAS f32x4*)(red + (wave * 2 + 0) * 256 + lane * 4) = a0;
;         *(LAS f32x4*)(red + (wave * 2 + 1) * 256 + lane * 4) = a1;
;         __syncthreads();
;         { const int b = tid >> 8, col = tid & 255; float s = p.ada_b[l * 6144 + cgi * 256 + col];
; #pragma unroll
;           for (int w = 0; w < 8; ++w) s += red[(w * 2 + b) * 256 + col];
;           mod[(size_t)(l * 2 + b) * 6144 + cgi * 256 + col] = s; }
	v_pk_fma_f32 v[4:5], v[58:59], v[78:79], v[4:5] op_sel_hi:[1,0,1]
	v_pk_fma_f32 v[2:3], v[56:57], v[78:79], v[2:3] op_sel_hi:[1,0,1]
	v_pk_fma_f32 v[8:9], v[58:59], v[80:81], v[8:9] op_sel_hi:[1,0,1]
	v_pk_fma_f32 v[6:7], v[56:57], v[80:81], v[6:7] op_sel_hi:[1,0,1]
	v_mov_b32_e32 v14, s18
	s_add_i32 s18, s18, 32
	ds_read_b128 v[60:63], v14
	ds_read_b128 v[64:67], v14 offset:8192
	ds_read_b128 v[68:71], v14 offset:16
	ds_read_b128 v[72:75], v14 offset:8208
	s_waitcnt lgkmcnt(3)
	v_mov_b32_e32 v14, v63
	s_waitcnt lgkmcnt(2)
	v_mov_b32_e32 v76, v67
	s_waitcnt lgkmcnt(1)
	v_mov_b32_e32 v78, v71
	s_waitcnt lgkmcnt(0)
	v_mov_b32_e32 v80, v75
	v_lshl_add_u64 v[18:19], v[18:19], 0, s[26:27]
	s_waitcnt vmcnt(7)
	v_pk_fma_f32 v[4:5], v[110:111], v[60:61], v[4:5] op_sel_hi:[1,0,1]
	v_pk_fma_f32 v[2:3], v[108:109], v[60:61], v[2:3] op_sel_hi:[1,0,1]
	v_pk_fma_f32 v[8:9], v[110:111], v[64:65], v[8:9] op_sel_hi:[1,0,1]
	v_pk_fma_f32 v[6:7], v[108:109], v[64:65], v[6:7] op_sel_hi:[1,0,1]
	s_waitcnt vmcnt(6)
	v_pk_fma_f32 v[4:5], v[114:115], v[60:61], v[4:5] op_sel:[0,1,0]
	v_pk_fma_f32 v[2:3], v[112:113], v[60:61], v[2:3] op_sel:[0,1,0]
	v_pk_fma_f32 v[8:9], v[114:115], v[64:65], v[8:9] op_sel:[0,1,0]
	v_pk_fma_f32 v[6:7], v[112:113], v[64:65], v[6:7] op_sel:[0,1,0]
	s_waitcnt vmcnt(5)
	v_pk_fma_f32 v[4:5], v[118:119], v[62:63], v[4:5] op_sel_hi:[1,0,1]
	v_pk_fma_f32 v[2:3], v[116:117], v[62:63], v[2:3] op_sel_hi:[1,0,1]
	v_pk_fma_f32 v[8:9], v[118:119], v[66:67], v[8:9] op_sel_hi:[1,0,1]
	v_pk_fma_f32 v[6:7], v[116:117], v[66:67], v[6:7] op_sel_hi:[1,0,1]
	s_waitcnt vmcnt(4)
	v_pk_fma_f32 v[4:5], v[122:123], v[14:15], v[4:5] op_sel_hi:[1,0,1]
	v_pk_fma_f32 v[2:3], v[120:121], v[14:15], v[2:3] op_sel_hi:[1,0,1]
	v_pk_fma_f32 v[8:9], v[122:123], v[76:77], v[8:9] op_sel_hi:[1,0,1]
	v_pk_fma_f32 v[6:7], v[120:121], v[76:77], v[6:7] op_sel_hi:[1,0,1]
	s_waitcnt vmcnt(3)
	v_pk_fma_f32 v[4:5], v[126:127], v[68:69], v[4:5] op_sel_hi:[1,0,1]
	v_pk_fma_f32 v[2:3], v[124:125], v[68:69], v[2:3] op_sel_hi:[1,0,1]
	v_pk_fma_f32 v[8:9], v[126:127], v[72:73], v[8:9] op_sel_hi:[1,0,1]
	v_pk_fma_f32 v[6:7], v[124:125], v[72:73], v[6:7] op_sel_hi:[1,0,1]
	s_waitcnt vmcnt(2)
	v_pk_fma_f32 v[4:5], v[130:131], v[68:69], v[4:5] op_sel:[0,1,0]
	v_pk_fma_f32 v[2:3], v[128:129], v[68:69], v[2:3] op_sel:[0,1,0]
	v_pk_fma_f32 v[8:9], v[130:131], v[72:73], v[8:9] op_sel:[0,1,0]
	v_pk_fma_f32 v[6:7], v[128:129], v[72:73], v[6:7] op_sel:[0,1,0]
	s_waitcnt vmcnt(1)
	v_pk_fma_f32 v[4:5], v[134:135], v[70:71], v[4:5] op_sel_hi:[1,0,1]
	v_pk_fma_f32 v[2:3], v[132:133], v[70:71], v[2:3] op_sel_hi:[1,0,1]
	v_pk_fma_f32 v[8:9], v[134:135], v[74:75], v[8:9] op_sel_hi:[1,0,1]
	v_pk_fma_f32 v[6:7], v[132:133], v[74:75], v[6:7] op_sel_hi:[1,0,1]
	s_waitcnt vmcnt(0)
	v_pk_fma_f32 v[4:5], v[138:139], v[78:79], v[4:5] op_sel_hi:[1,0,1]
	v_pk_fma_f32 v[2:3], v[136:137], v[78:79], v[2:3] op_sel_hi:[1,0,1]
	v_pk_fma_f32 v[8:9], v[138:139], v[80:81], v[8:9] op_sel_hi:[1,0,1]
	v_pk_fma_f32 v[6:7], v[136:137], v[80:81], v[6:7] op_sel_hi:[1,0,1]
	s_cmp_lt_i32 s19, s41
	s_cbranch_scc1 .LBB0_22
	s_mul_i32 s18, s0, 0xffffffe8
	s_add_i32 s18, s18, s51
	s_lshl_b32 s18, s18, 8
	s_add_i32 s1, s18, s1
	ds_write_b128 v13, v[2:5] offset:16384
	ds_write_b128 v13, v[6:9] offset:17408
	v_or_b32_e32 v2, s1, v12
	v_ashrrev_i32_e32 v3, 31, v2
	v_lshl_add_u64 v[2:3], v[2:3], 2, s[88:89]
	s_waitcnt lgkmcnt(0)
	s_barrier
	global_load_dword v27, v[2:3], off
	ds_read2st64_b32 v[2:3], v21 offset0:64 offset1:72
	ds_read2st64_b32 v[4:5], v21 offset0:80 offset1:88
	ds_read2st64_b32 v[6:7], v21 offset0:96 offset1:104
	ds_read2st64_b32 v[8:9], v21 offset0:112 offset1:120
	v_lshl_add_u32 v28, s0, 1, v20
	v_mov_b64_e32 v[18:19], s[62:63]
	v_mad_i64_i32 v[18:19], s[0:1], v28, s44, v[18:19]
	s_ashr_i32 s19, s18, 31
	v_lshlrev_b32_e32 v14, 2, v12
	s_add_i32 s45, s45, s46
	s_add_i32 s51, s51, s28
	v_lshl_add_u64 v[18:19], s[18:19], 2, v[18:19]
	v_lshl_add_u64 v[18:19], v[18:19], 0, v[14:15]
	s_cmpk_gt_i32 s51, 0x5f
	s_waitcnt vmcnt(0) lgkmcnt(3)
	v_add_f32_e32 v2, v27, v2
	v_add_f32_e32 v2, v2, v3
	s_waitcnt lgkmcnt(2)
	v_add_f32_e32 v2, v2, v4
	v_add_f32_e32 v2, v2, v5
	s_waitcnt lgkmcnt(1)
	v_add_f32_e32 v2, v2, v6
	v_add_f32_e32 v2, v2, v7
	s_waitcnt lgkmcnt(0)
	v_add_f32_e32 v2, v2, v8
	v_add_f32_e32 v2, v2, v9
	global_store_dword v[18:19], v2, off
	s_cbranch_scc0 .LBB0_7
